# speedup vs baseline: 1.0250x; 1.0013x over previous
; __device__ __forceinline__ float silu_f(float x) { return x * __builtin_amdgcn_rcpf(1.f + __expf(-x)); }
;     __device__ __forceinline__ void operator()(const f32x4 (&acc)[2][2][4][2], const Unit& u, int wr, int wc, int fr, int fq) const {
;         const int r0 = u.pm * BM + wr * 64 + fr, ch = 64 * u.pn + 16 * wc + 4 * fq, lane = fq * 16 + fr;
;         float rstd[2][4];
; #pragma unroll
;         for (int ai = 0; ai < 2; ++ai)
; #pragma unroll
;             for (int m = 0; m < 4; ++m) rstd[ai][m] = (float)ss[r0 + ai * HALF + m * 16] * (1.f / 16777216.f);
;         const f32x4 w0 = *(const f32x4*)(cw + ch), w1 = *(const f32x4*)(cw + 2048 + ch), w2 = *(const f32x4*)(cw + 4096 + ch);
;         const bool fuse = u.pm != 96;
;         const int lr = (lane & 48) | ((fr + 15) & 15), ll = (lane & 48) | ((fr + 1) & 15);
; #pragma unroll
;         for (int ai = 0; ai < 2; ++ai) {
;             f32x4 g[4], cu[4];
; #pragma unroll
;             for (int m = 0; m < 4; ++m) {
;                 const float rs = __builtin_amdgcn_rsqf(rstd[ai][m] * (1.f / 2048.f) + 1e-6f);
;                 const f32x4 b = acc[ai][0][m][0] * rs, z = acc[ai][0][m][1] * rs, c = acc[ai][1][m][0] * rs, uu = acc[ai][1][m][1] * rs;
; #pragma unroll
;                 for (int j = 0; j < 4; ++j) { g[m][j] = b[j] * silu_f(z[j]); cu[m][j] = c[j] * uu[j]; }
;             }
.LBB0_301:
	v_lshl_add_u32 v148, s72, 8, v164
	v_ashrrev_i32_e32 v149, 31, v148
	v_lshl_add_u64 v[64:65], v[148:149], 3, s[92:93]
	global_load_dwordx2 v[66:67], v[64:65], off
	global_load_dwordx2 v[194:195], v[64:65], off offset:128
	global_load_dwordx2 v[196:197], v[64:65], off offset:256
	global_load_dwordx2 v[198:199], v[64:65], off offset:384
	v_lshl_or_b32 v146, s64, 6, v166
	v_ashrrev_i32_e32 v147, 31, v146
	v_lshlrev_b64 v[72:73], 2, v[146:147]
	s_cmpk_lg_i32 s72, 0x60
	v_or_b32_e32 v150, 16, v148
	v_or_b32_e32 v154, 32, v148
	v_or_b32_e32 v160, 48, v148
	s_cselect_b64 s[72:73], -1, 0
	v_ashrrev_i32_e32 v151, 31, v150
	v_ashrrev_i32_e32 v155, 31, v154
	v_ashrrev_i32_e32 v161, 31, v160
	s_and_b64 vcc, exec, s[72:73]
	s_movk_i32 s94, 0x5fff
	s_waitcnt vmcnt(3)
	v_ffbh_u32_e32 v68, v67
	v_min_u32_e32 v68, 32, v68
	v_lshlrev_b64 v[66:67], v68, v[66:67]
	v_min_u32_e32 v66, 1, v66
	v_or_b32_e32 v66, v67, v66
	v_cvt_f32_u32_e32 v66, v66
	v_sub_u32_e32 v67, 32, v68
	v_ldexp_f32 v66, v66, v67
	v_mul_f32_e32 v173, 0x33800000, v66
	v_fmamk_f32 v173, v173, 0x3a000000, v227
	v_rsq_f32_e32 v173, v173
	s_waitcnt vmcnt(2)
	v_ffbh_u32_e32 v68, v195
	v_min_u32_e32 v68, 32, v68
	v_lshlrev_b64 v[194:195], v68, v[194:195]
	v_min_u32_e32 v194, 1, v194
	v_or_b32_e32 v194, v195, v194
	v_cvt_f32_u32_e32 v194, v194
	v_sub_u32_e32 v195, 32, v68
	v_mul_f32_e32 v132, v132, v173
	v_mul_f32_e32 v174, 0xbfb8aa3b, v132
	v_ldexp_f32 v194, v194, v195
	v_mul_f32_e32 v172, 0x33800000, v194
	v_exp_f32_e32 v174, v174
	v_mul_f32_e32 v136, v136, v173
	v_mul_f32_e32 v133, v133, v173
	v_mul_f32_e32 v128, v128, v173
	v_add_f32_e32 v174, 1.0, v174
	v_rcp_f32_e32 v174, v174
	v_mul_f32_e32 v124, v124, v173
	v_mul_f32_e32 v124, v128, v124
	v_mul_f32_e32 v128, v137, v173
	v_mul_f32_e32 v132, v132, v174
	v_mul_f32_e32 v132, v136, v132
	v_mul_f32_e32 v136, 0xbfb8aa3b, v133
	v_exp_f32_e32 v136, v136
	v_mul_f32_e32 v129, v129, v173
	v_mul_f32_e32 v125, v125, v173
	v_mul_f32_e32 v125, v129, v125
	v_add_f32_e32 v136, 1.0, v136
	v_rcp_f32_e32 v136, v136
	v_mul_f32_e32 v129, v138, v173
	v_mul_f32_e32 v131, v131, v173
	v_mul_f32_e32 v127, v127, v173
	v_mul_f32_e32 v133, v133, v136
	v_mul_f32_e32 v128, v128, v133
	v_mul_f32_e32 v133, v134, v173
	v_mul_f32_e32 v134, 0xbfb8aa3b, v133
	v_exp_f32_e32 v134, v134
	v_mul_f32_e32 v127, v131, v127
	v_fmamk_f32 v131, v172, 0x3a000000, v227
	v_rsq_f32_e32 v131, v131
	v_add_f32_e32 v134, 1.0, v134
	v_rcp_f32_e32 v134, v134
	v_mul_f32_e32 v130, v130, v173
	v_mul_f32_e32 v126, v126, v173
	v_mul_f32_e32 v126, v130, v126
	v_mul_f32_e32 v133, v133, v134
	v_mul_f32_e32 v129, v129, v133
	v_mul_f32_e32 v133, v135, v173
	v_mul_f32_e32 v134, 0xbfb8aa3b, v133
	v_exp_f32_e32 v134, v134
	v_mul_f32_e32 v130, v139, v173
	v_mul_f32_e32 v116, v116, v131
	v_mul_f32_e32 v120, v120, v131
	v_add_f32_e32 v134, 1.0, v134
	v_rcp_f32_e32 v134, v134
	v_mul_f32_e32 v117, v117, v131
	v_mul_f32_e32 v112, v112, v131
	v_mul_f32_e32 v108, v108, v131
	v_mul_f32_e32 v133, v133, v134
	v_mul_f32_e32 v130, v130, v133
	v_mul_f32_e32 v133, 0xbfb8aa3b, v116
	v_exp_f32_e32 v133, v133
	v_mul_f32_e32 v108, v112, v108
	v_mul_f32_e32 v112, v121, v131
	v_mul_f32_e32 v113, v113, v131
	v_add_f32_e32 v133, 1.0, v133
	v_rcp_f32_e32 v133, v133
	v_mul_f32_e32 v109, v109, v131
	v_mul_f32_e32 v109, v113, v109
	v_mul_f32_e32 v113, v122, v131
	v_mul_f32_e32 v116, v116, v133
	v_mul_f32_e32 v116, v120, v116
	v_mul_f32_e32 v120, 0xbfb8aa3b, v117
	v_exp_f32_e32 v120, v120
	v_mul_f32_e32 v115, v115, v131
	v_mul_f32_e32 v111, v111, v131
	v_mul_f32_e32 v111, v115, v111
	v_add_f32_e32 v120, 1.0, v120
	v_rcp_f32_e32 v120, v120
	v_mul_f32_e32 v114, v114, v131
	v_mul_f32_e32 v110, v110, v131
	v_mul_f32_e32 v110, v114, v110
	v_mul_f32_e32 v117, v117, v120
	v_mul_f32_e32 v112, v112, v117
	v_mul_f32_e32 v117, v118, v131
	v_mul_f32_e32 v118, 0xbfb8aa3b, v117
	v_exp_f32_e32 v118, v118
	v_mul_f32_e32 v114, v123, v131
	s_waitcnt vmcnt(1)
	v_ffbh_u32_e32 v68, v197
	v_min_u32_e32 v68, 32, v68
	v_lshlrev_b64 v[196:197], v68, v[196:197]
	v_min_u32_e32 v196, 1, v196
	v_or_b32_e32 v196, v197, v196
	v_cvt_f32_u32_e32 v196, v196
	v_sub_u32_e32 v197, 32, v68
	v_add_f32_e32 v118, 1.0, v118
	v_rcp_f32_e32 v118, v118
	v_ldexp_f32 v196, v196, v197
	v_mul_f32_e32 v171, 0x33800000, v196
	v_mul_f32_e32 v117, v117, v118
	v_mul_f32_e32 v113, v113, v117
	v_mul_f32_e32 v117, v119, v131
	v_mul_f32_e32 v118, 0xbfb8aa3b, v117
	v_exp_f32_e32 v118, v118
	v_fmamk_f32 v115, v171, 0x3a000000, v227
	v_rsq_f32_e32 v115, v115
	global_load_dwordx2 v[162:163], v[64:65], off offset:1024
	global_load_dwordx2 v[158:159], v[64:65], off offset:1152
	global_load_dwordx2 v[156:157], v[64:65], off offset:1280
	global_load_dwordx2 v[152:153], v[64:65], off offset:1408
	v_add_f32_e32 v118, 1.0, v118
	v_rcp_f32_e32 v118, v118
	v_mul_f32_e32 v100, v100, v115
	v_mul_f32_e32 v104, v104, v115
	v_mul_f32_e32 v96, v96, v115
	v_mul_f32_e32 v117, v117, v118
	v_mul_f32_e32 v114, v114, v117
	v_mul_f32_e32 v117, 0xbfb8aa3b, v100
	v_exp_f32_e32 v117, v117
	v_mul_f32_e32 v92, v92, v115
	v_mul_f32_e32 v93, v93, v115
	v_lshl_add_u64 v[64:65], s[56:57], 0, v[72:73]
	v_add_f32_e32 v117, 1.0, v117
	v_rcp_f32_e32 v117, v117
	s_waitcnt vmcnt(4)
; __device__ __forceinline__ float silu_f(float x) { return x * __builtin_amdgcn_rcpf(1.f + __expf(-x)); }
;     __device__ __forceinline__ void operator()(const f32x4 (&acc)[2][2][4][2], const Unit& u, int wr, int wc, int fr, int fq) const {
;     ...
;             for (int m = 0; m < 4; ++m) rstd[ai][m] = (float)ss[r0 + ai * HALF + m * 16] * (1.f / 16777216.f);
;         const f32x4 w0 = *(const f32x4*)(cw + ch), w1 = *(const f32x4*)(cw + 2048 + ch), w2 = *(const f32x4*)(cw + 4096 + ch);
;         const bool fuse = u.pm != 96;
;         const int lr = (lane & 48) | ((fr + 15) & 15), ll = (lane & 48) | ((fr + 1) & 15);
; #pragma unroll
;         for (int ai = 0; ai < 2; ++ai) {
;             f32x4 g[4], cu[4];
; #pragma unroll
;             for (int m = 0; m < 4; ++m) {
;                 const float rs = __builtin_amdgcn_rsqf(rstd[ai][m] * (1.f / 2048.f) + 1e-6f);
;                 const f32x4 b = acc[ai][0][m][0] * rs, z = acc[ai][0][m][1] * rs, c = acc[ai][1][m][0] * rs, uu = acc[ai][1][m][1] * rs;
; #pragma unroll
;                 for (int j = 0; j < 4; ++j) { g[m][j] = b[j] * silu_f(z[j]); cu[m][j] = c[j] * uu[j]; }
;             }
;             if (fuse) {
;                 f32x4 R[4], L[4];
; #pragma unroll
;                 for (int m = 0; m < 4; ++m)
; #pragma unroll
;                     for (int j = 0; j < 4; ++j) { R[m][j] = __shfl(cu[m][j], lr); L[m][j] = __shfl(cu[m][j], ll); }
; #pragma unroll
;                 for (int m = 0; m < 4; ++m) {
;                     const int r = r0 + ai * HALF + m * 16;
;                     const f32x4 prev = (fr == 0) ? R[m > 0 ? m - 1 : 0] : R[m], next = (fr == 15) ? L[m < 3 ? m + 1 : 3] : L[m];
;                     const bool edge = (m == 0 && fr == 0) || (m == 3 && fr == 15);
;                     f32x4 y;
; #pragma unroll
;                     for (int j = 0; j < 4; ++j) { const float t = g[m][j] * (prev[j] * w0[j] + cu[m][j] * w1[j] + next[j] * w2[j]); y[j] = edge ? g[m][j] : t; }
;                     const size_t off = (size_t)r * 2048 + ch;
;                     u32x2 o1; o1.x = cvt_pk_bf16(y[0], y[1]); o1.y = cvt_pk_bf16(y[2], y[3]);
;                     *(u32x2*)(G + off) = o1;
;                     if ((m == 0 && fr <= 1) || (m == 3 && fr >= 14)) { u32x2 o2; o2.x = cvt_pk_bf16(cu[m][0], cu[m][1]); o2.y = cvt_pk_bf16(cu[m][2], cu[m][3]); *(u32x2*)(CU + off) = o2; }
	v_ffbh_u32_e32 v68, v199
	v_mul_f32_e32 v100, v100, v117
	v_mul_f32_e32 v104, v104, v100
	v_mul_f32_e32 v100, v96, v92
	v_mul_f32_e32 v96, v101, v115
	v_mul_f32_e32 v101, 0xbfb8aa3b, v96
	v_exp_f32_e32 v101, v101
	v_min_u32_e32 v68, 32, v68
	v_lshlrev_b64 v[198:199], v68, v[198:199]
	v_min_u32_e32 v198, 1, v198
	v_add_f32_e32 v101, 1.0, v101
	v_rcp_f32_e32 v101, v101
	v_or_b32_e32 v198, v199, v198
	v_cvt_f32_u32_e32 v198, v198
	v_mul_f32_e32 v92, v105, v115
	v_mul_f32_e32 v96, v96, v101
	v_sub_u32_e32 v199, 32, v68
	v_mul_f32_e32 v105, v92, v96
	v_mul_f32_e32 v92, v97, v115
	v_ldexp_f32 v198, v198, v199
	v_lshl_add_u64 v[68:69], s[60:61], 0, v[72:73]
	v_lshl_add_u64 v[72:73], s[62:63], 0, v[72:73]
	v_mul_f32_e32 v101, v92, v93
	v_mul_f32_e32 v93, v102, v115
	v_mul_f32_e32 v170, 0x33800000, v198
	global_load_dwordx4 v[64:67], v[64:65], off
	v_mul_f32_e32 v96, 0xbfb8aa3b, v93
	global_load_dwordx4 v[68:71], v[68:69], off
	v_exp_f32_e32 v96, v96
	global_load_dwordx4 v[72:75], v[72:73], off
	v_mul_f32_e32 v92, v106, v115
	v_add_f32_e32 v96, 1.0, v96
	v_rcp_f32_e32 v96, v96
	s_nop 0
	v_mul_f32_e32 v93, v93, v96
	v_mul_f32_e32 v102, v92, v93
	v_mul_f32_e32 v92, v98, v115
	v_mul_f32_e32 v93, v94, v115
	v_mul_f32_e32 v98, v92, v93
	v_mul_f32_e32 v93, v103, v115
	v_mul_f32_e32 v94, 0xbfb8aa3b, v93
	v_exp_f32_e32 v94, v94
	v_mul_f32_e32 v92, v107, v115
	v_add_f32_e32 v94, 1.0, v94
	v_rcp_f32_e32 v94, v94
	s_nop 0
	v_mul_f32_e32 v93, v93, v94
	v_mul_f32_e32 v103, v92, v93
	v_mul_f32_e32 v92, v99, v115
	v_mul_f32_e32 v93, v95, v115
	v_mul_f32_e32 v99, v92, v93
	v_fmamk_f32 v92, v170, 0x3a000000, v227
	v_rsq_f32_e32 v92, v92
	s_nop 0
	v_mul_f32_e32 v84, v84, v92
	v_mul_f32_e32 v93, 0xbfb8aa3b, v84
	v_exp_f32_e32 v93, v93
	v_mul_f32_e32 v80, v80, v92
	v_mul_f32_e32 v76, v76, v92
	v_mul_f32_e32 v88, v88, v92
	v_add_f32_e32 v93, 1.0, v93
	v_rcp_f32_e32 v93, v93
	v_mul_f32_e32 v77, v77, v92
	v_mul_f32_e32 v78, v78, v92
	v_mul_f32_e32 v84, v84, v93
	v_mul_f32_e32 v93, v80, v76
	v_mul_f32_e32 v80, v85, v92
	v_mul_f32_e32 v106, v88, v84
	v_mul_f32_e32 v84, 0xbfb8aa3b, v80
	v_exp_f32_e32 v84, v84
	v_mul_f32_e32 v76, v89, v92
	v_add_f32_e32 v84, 1.0, v84
	v_rcp_f32_e32 v84, v84
	s_nop 0
	v_mul_f32_e32 v80, v80, v84
	v_mul_f32_e32 v107, v76, v80
	v_mul_f32_e32 v80, v86, v92
	v_mul_f32_e32 v76, v81, v92
	v_mul_f32_e32 v81, 0xbfb8aa3b, v80
	v_exp_f32_e32 v81, v81
	v_mul_f32_e32 v77, v76, v77
	v_mul_f32_e32 v76, v90, v92
	v_add_f32_e32 v81, 1.0, v81
	v_rcp_f32_e32 v81, v81
	s_nop 0
	v_mul_f32_e32 v80, v80, v81
	v_mul_f32_e32 v115, v76, v80
	v_mul_f32_e32 v76, v82, v92
	v_mul_f32_e32 v81, v76, v78
	v_mul_f32_e32 v78, v87, v92
	v_mul_f32_e32 v80, 0xbfb8aa3b, v78
	v_exp_f32_e32 v80, v80
	v_mul_f32_e32 v76, v91, v92
	v_add_f32_e32 v80, 1.0, v80
	v_rcp_f32_e32 v80, v80
	s_nop 0
	v_mul_f32_e32 v78, v78, v80
	v_mul_f32_e32 v117, v76, v78
	v_mul_f32_e32 v76, v83, v92
	v_mul_f32_e32 v78, v79, v92
	v_lshlrev_b64 v[82:83], 11, v[148:149]
	v_mul_f32_e32 v79, v76, v78
	v_lshl_add_u64 v[82:83], v[82:83], 0, v[146:147]
	s_cbranch_vccz .LBB0_307
	v_and_b32_e32 v76, 64, v232
	v_or_b32_e32 v78, v76, v167
	v_or_b32_e32 v76, v76, v168
	v_lshlrev_b32_e32 v78, 2, v78
	v_lshlrev_b32_e32 v84, 2, v76
	s_nop 1
	v_mov_b32_dpp v88, v124 row_ror:1 row_mask:0xf bank_mask:0xf
	v_mov_b32_dpp v85, v124 row_ror:15 row_mask:0xf bank_mask:0xf
	v_mov_b32_dpp v86, v125 row_ror:15 row_mask:0xf bank_mask:0xf
	v_mov_b32_dpp v87, v126 row_ror:15 row_mask:0xf bank_mask:0xf
	v_mov_b32_dpp v171, v108 row_ror:15 row_mask:0xf bank_mask:0xf
	v_mov_b32_dpp v172, v109 row_ror:15 row_mask:0xf bank_mask:0xf
	v_mov_b32_dpp v173, v110 row_ror:15 row_mask:0xf bank_mask:0xf
	v_mov_b32_dpp v89, v125 row_ror:1 row_mask:0xf bank_mask:0xf
	v_mov_b32_dpp v96, v126 row_ror:1 row_mask:0xf bank_mask:0xf
	v_mov_b32_dpp v97, v127 row_ror:1 row_mask:0xf bank_mask:0xf
	v_mov_b32_dpp v90, v127 row_ror:15 row_mask:0xf bank_mask:0xf
	v_mov_b32_dpp v134, v108 row_ror:1 row_mask:0xf bank_mask:0xf
	v_mov_b32_dpp v135, v109 row_ror:1 row_mask:0xf bank_mask:0xf
	v_mov_b32_dpp v137, v110 row_ror:1 row_mask:0xf bank_mask:0xf
	v_mov_b32_dpp v139, v111 row_ror:1 row_mask:0xf bank_mask:0xf
	v_mov_b32_dpp v174, v111 row_ror:15 row_mask:0xf bank_mask:0xf
	v_mov_b32_dpp v118, v100 row_ror:1 row_mask:0xf bank_mask:0xf
	v_mov_b32_dpp v136, v100 row_ror:15 row_mask:0xf bank_mask:0xf
	v_mov_b32_dpp v119, v101 row_ror:1 row_mask:0xf bank_mask:0xf
	v_mov_b32_dpp v138, v101 row_ror:15 row_mask:0xf bank_mask:0xf
	v_mov_b32_dpp v120, v98 row_ror:1 row_mask:0xf bank_mask:0xf
	v_mov_b32_dpp v149, v98 row_ror:15 row_mask:0xf bank_mask:0xf
	v_mov_b32_dpp v122, v99 row_ror:1 row_mask:0xf bank_mask:0xf
	v_mov_b32_dpp v170, v99 row_ror:15 row_mask:0xf bank_mask:0xf
	v_mov_b32_dpp v121, v93 row_ror:1 row_mask:0xf bank_mask:0xf
	v_mov_b32_dpp v92, v93 row_ror:15 row_mask:0xf bank_mask:0xf
	v_mov_b32_dpp v123, v77 row_ror:1 row_mask:0xf bank_mask:0xf
	v_mov_b32_dpp v76, v77 row_ror:15 row_mask:0xf bank_mask:0xf
	v_mov_b32_dpp v131, v81 row_ror:1 row_mask:0xf bank_mask:0xf
	v_mov_b32_dpp v80, v81 row_ror:15 row_mask:0xf bank_mask:0xf
	v_mov_b32_dpp v133, v79 row_ror:1 row_mask:0xf bank_mask:0xf
	v_mov_b32_dpp v78, v79 row_ror:15 row_mask:0xf bank_mask:0xf
	s_waitcnt lgkmcnt(14)
	v_cndmask_b32_e64 v95, v87, v173, s[6:7]
	v_cndmask_b32_e64 v91, v86, v172, s[6:7]
	v_cndmask_b32_e64 v87, v85, v171, s[6:7]
	s_waitcnt vmcnt(2)
	v_mov_b32_e32 v84, v64
	s_waitcnt vmcnt(0)
	v_mov_b32_e32 v85, v72
	v_mov_b32_e32 v86, v88
	v_pk_mul_f32 v[86:87], v[84:85], v[86:87]
	v_cndmask_b32_e64 v177, v90, v174, s[6:7]
	v_fma_f32 v86, v124, v68, v86
	v_add_f32_e32 v86, v86, v87
	v_mul_f32_e32 v86, v132, v86
	v_cndmask_b32_e64 v175, v86, v132, s[4:5]
	v_mov_b32_e32 v86, v65
	v_mov_b32_e32 v87, v73
	v_mov_b32_e32 v90, v89
	v_pk_mul_f32 v[90:91], v[86:87], v[90:91]
	v_mov_b32_e32 v94, v96
	v_fma_f32 v90, v125, v69, v90
	v_add_f32_e32 v90, v90, v91
	v_mul_f32_e32 v90, v128, v90
	v_cndmask_b32_e64 v178, v90, v128, s[4:5]
	v_mov_b32_e32 v90, v66
	v_mov_b32_e32 v91, v74
	v_pk_mul_f32 v[94:95], v[90:91], v[94:95]
	v_mov_b32_e32 v176, v97
	v_fma_f32 v94, v126, v70, v94
	v_add_f32_e32 v94, v94, v95
	v_mul_f32_e32 v94, v129, v94
	v_cndmask_b32_e64 v179, v94, v129, s[4:5]
	v_mov_b32_e32 v94, v67
	v_mov_b32_e32 v95, v75
	v_pk_mul_f32 v[176:177], v[94:95], v[176:177]
	s_nop 0
	v_fma_f32 v176, v127, v71, v176
	v_add_f32_e32 v176, v176, v177
	v_mul_f32_e32 v176, v130, v176
	v_cndmask_b32_e64 v177, v176, v130, s[4:5]
	v_cvt_pk_bf16_f32 v176, v175, v178
	v_cvt_pk_bf16_f32 v177, v179, v177
	v_lshl_add_u64 v[178:179], v[82:83], 1, s[48:49]
	global_store_dwordx2 v[178:179], v[176:177], off
	s_and_saveexec_b64 s[64:65], s[8:9]
	s_cbranch_execz .LBB0_304
	v_lshl_add_u64 v[178:179], v[82:83], 1, s[16:17]
	v_cvt_pk_bf16_f32 v176, v124, v125
	v_cvt_pk_bf16_f32 v177, v126, v127
	global_store_dwordx2 v[178:179], v[176:177], off

;     __device__ __forceinline__ void operator()(const f32x4 (&acc)[2][2][4][2], const Unit& u, int wr, int wc, int fr, int fq) const {
;         const int pn = u.pn, r0 = u.pm * BM + wr * 64 + fr;
;         float rstd[2][4];
; #pragma unroll
;         for (int ai = 0; ai < 2; ++ai)
; #pragma unroll
;             for (int m = 0; m < 4; ++m) rstd[ai][m] = (float)ss[r0 + ai * HALF + m * 16] * (1.f / 16777216.f);
;         if (pn < 10) {
.LBB0_347:
	s_lshl_b32 s57, s6, 8
	s_add_i32 s57, s57, s75
	v_or_b32_e32 v178, s57, v165
	v_ashrrev_i32_e32 v179, 31, v178
	v_lshl_add_u64 v[128:129], v[178:179], 3, s[92:93]
	global_load_dwordx2 v[130:131], v[128:129], off
	global_load_dwordx2 v[132:133], v[128:129], off offset:128
	global_load_dwordx2 v[134:135], v[128:129], off offset:256
	global_load_dwordx2 v[136:137], v[128:129], off offset:384
	global_load_dwordx2 v[138:139], v[128:129], off offset:1024
	global_load_dwordx2 v[140:141], v[128:129], off offset:1152
	global_load_dwordx2 v[142:143], v[128:129], off offset:1280
	global_load_dwordx2 v[144:145], v[128:129], off offset:1408
	v_or_b32_e32 v194, 16, v178
	v_or_b32_e32 v186, 32, v178
	v_or_b32_e32 v184, 48, v178
	v_add_u32_e32 v182, 0x80, v178
	v_add_u32_e32 v180, 0x90, v178
	v_add_u32_e32 v176, 0xa0, v178
	v_add_u32_e32 v174, 0xb0, v178
	v_ashrrev_i32_e32 v195, 31, v194
	v_ashrrev_i32_e32 v187, 31, v186
	v_ashrrev_i32_e32 v185, 31, v184
	v_ashrrev_i32_e32 v183, 31, v182
	v_ashrrev_i32_e32 v181, 31, v180
	v_ashrrev_i32_e32 v177, 31, v176
	v_ashrrev_i32_e32 v175, 31, v174
	s_mov_b64 s[6:7], -1
	s_cmp_lt_i32 s52, 10
	s_waitcnt vmcnt(7)
	v_ffbh_u32_e32 v146, v131
	v_min_u32_e32 v146, 32, v146
	v_lshlrev_b64 v[130:131], v146, v[130:131]
	v_min_u32_e32 v130, 1, v130
	v_or_b32_e32 v130, v131, v130
	v_cvt_f32_u32_e32 v130, v130
	v_sub_u32_e32 v147, 32, v146
	v_ldexp_f32 v130, v130, v147
	v_mul_f32_e32 v130, 0x33800000, v130
	s_waitcnt vmcnt(6)
	v_ffbh_u32_e32 v146, v133
	v_min_u32_e32 v146, 32, v146
	v_lshlrev_b64 v[132:133], v146, v[132:133]
	v_min_u32_e32 v132, 1, v132
	v_or_b32_e32 v132, v133, v132
	v_cvt_f32_u32_e32 v132, v132
	v_sub_u32_e32 v147, 32, v146
	v_ldexp_f32 v132, v132, v147
	v_mul_f32_e32 v211, 0x33800000, v132
	s_waitcnt vmcnt(5)
	v_ffbh_u32_e32 v146, v135
	v_min_u32_e32 v146, 32, v146
	v_lshlrev_b64 v[134:135], v146, v[134:135]
	v_min_u32_e32 v134, 1, v134
	v_or_b32_e32 v134, v135, v134
	v_cvt_f32_u32_e32 v134, v134
	v_sub_u32_e32 v147, 32, v146
	v_ldexp_f32 v134, v134, v147
	v_mul_f32_e32 v210, 0x33800000, v134
	s_waitcnt vmcnt(4)
	v_ffbh_u32_e32 v146, v137
	v_min_u32_e32 v146, 32, v146
	v_lshlrev_b64 v[136:137], v146, v[136:137]
	v_min_u32_e32 v136, 1, v136
	v_or_b32_e32 v136, v137, v136
	v_cvt_f32_u32_e32 v136, v136
	v_sub_u32_e32 v147, 32, v146
	v_ldexp_f32 v136, v136, v147
	v_mul_f32_e32 v209, 0x33800000, v136
	s_waitcnt vmcnt(3)
	v_ffbh_u32_e32 v146, v139
	v_min_u32_e32 v146, 32, v146
	v_lshlrev_b64 v[138:139], v146, v[138:139]
	v_min_u32_e32 v138, 1, v138
	v_or_b32_e32 v138, v139, v138
	v_cvt_f32_u32_e32 v138, v138
	v_sub_u32_e32 v147, 32, v146
	v_ldexp_f32 v138, v138, v147
	v_mul_f32_e32 v207, 0x33800000, v138
	s_waitcnt vmcnt(2)
	v_ffbh_u32_e32 v146, v141
	v_min_u32_e32 v146, 32, v146
	v_lshlrev_b64 v[140:141], v146, v[140:141]
	v_min_u32_e32 v140, 1, v140
	v_or_b32_e32 v140, v141, v140
	v_cvt_f32_u32_e32 v140, v140
	v_sub_u32_e32 v147, 32, v146
	v_ldexp_f32 v140, v140, v147
	v_mul_f32_e32 v206, 0x33800000, v140
	s_waitcnt vmcnt(1)
	v_ffbh_u32_e32 v146, v143
	v_min_u32_e32 v146, 32, v146
	v_lshlrev_b64 v[142:143], v146, v[142:143]
	v_min_u32_e32 v142, 1, v142
	v_or_b32_e32 v142, v143, v142
	v_cvt_f32_u32_e32 v142, v142
	v_sub_u32_e32 v147, 32, v146
	v_ldexp_f32 v142, v142, v147
	v_mul_f32_e32 v205, 0x33800000, v142
	s_waitcnt vmcnt(0)
	v_ffbh_u32_e32 v146, v145
	v_min_u32_e32 v146, 32, v146
	v_lshlrev_b64 v[144:145], v146, v[144:145]
	v_min_u32_e32 v144, 1, v144
	v_or_b32_e32 v144, v145, v144
	v_cvt_f32_u32_e32 v144, v144
	v_sub_u32_e32 v147, 32, v146
	v_ldexp_f32 v144, v144, v147
	v_mul_f32_e32 v208, 0x33800000, v144
	v_fmamk_f32 v128, v130, 0x3a000000, v227
	v_rsq_f32_e32 v196, v128
	s_cbranch_scc0 .LBB0_350
	s_and_b64 vcc, exec, s[6:7]
	s_cbranch_vccnz .LBB0_415
